# accumulator zeroing between units with 64-bit moves (half the instructions)
# speedup vs baseline: 1.0066x; 1.0031x over previous
.LBB0_552:
	s_mov_b32 s17, s9
	s_lshl_b64 s[20:21], s[16:17], 1
	s_add_u32 s20, s58, s20
	s_addc_u32 s21, s59, s21
	s_and_b64 s[22:23], s[6:7], exec
	s_mov_b32 s19, s9
	s_cselect_b32 s17, s21, s27
	s_cselect_b32 s54, s20, s26
	s_lshl_b64 s[22:23], s[18:19], 1
	s_add_u32 s22, s93, s22
	v_readlane_b32 s19, v250, 4
	s_addc_u32 s23, s19, s23
	s_and_b64 s[28:29], s[6:7], exec
	s_cselect_b32 s19, s23, s25
	s_cselect_b32 s55, s22, s24
	s_add_u32 s56, s24, 0x2c0000
	s_addc_u32 s57, s25, 0
	s_add_u32 s24, s26, 0x404000
	v_mov_b32_e32 v0, 0
	s_addc_u32 s25, s27, 0
	s_mov_b32 s62, -2
	v_mov_b32_e32 v1, 0
	v_mov_b64_e32 v[2:3], 0
	v_mov_b64_e32 v[4:5], 0
	v_mov_b64_e32 v[6:7], 0
	v_mov_b64_e32 v[8:9], 0
	v_mov_b64_e32 v[10:11], 0
	v_mov_b64_e32 v[12:13], 0
	v_mov_b64_e32 v[14:15], 0
	v_mov_b64_e32 v[16:17], 0
	v_mov_b64_e32 v[18:19], 0
	v_mov_b64_e32 v[20:21], 0
	v_mov_b64_e32 v[22:23], 0
	v_mov_b64_e32 v[24:25], 0
	v_mov_b64_e32 v[26:27], 0
	v_mov_b64_e32 v[28:29], 0
	v_mov_b64_e32 v[30:31], 0
	v_mov_b64_e32 v[32:33], 0
	v_mov_b64_e32 v[34:35], 0
	v_mov_b64_e32 v[36:37], 0
	v_mov_b64_e32 v[38:39], 0
	v_mov_b64_e32 v[40:41], 0
	v_mov_b64_e32 v[42:43], 0
	v_mov_b64_e32 v[44:45], 0
	v_mov_b64_e32 v[46:47], 0
	v_mov_b64_e32 v[48:49], 0
	v_mov_b64_e32 v[50:51], 0
	v_mov_b64_e32 v[52:53], 0
	v_mov_b64_e32 v[54:55], 0
	v_mov_b64_e32 v[56:57], 0
	v_mov_b64_e32 v[58:59], 0
	v_mov_b64_e32 v[60:61], 0
	v_mov_b64_e32 v[62:63], 0
	v_mov_b64_e32 v[64:65], 0
	v_mov_b64_e32 v[66:67], 0
	v_mov_b64_e32 v[68:69], 0
	v_mov_b64_e32 v[70:71], 0
	v_mov_b64_e32 v[72:73], 0
	v_mov_b64_e32 v[74:75], 0
	v_mov_b64_e32 v[76:77], 0
	v_mov_b64_e32 v[78:79], 0
	v_mov_b64_e32 v[80:81], 0
	v_mov_b64_e32 v[82:83], 0
	v_mov_b64_e32 v[84:85], 0
	v_mov_b64_e32 v[86:87], 0
	v_mov_b64_e32 v[88:89], 0
	v_mov_b64_e32 v[90:91], 0
	v_mov_b64_e32 v[92:93], 0
	v_mov_b64_e32 v[94:95], 0
	v_mov_b64_e32 v[96:97], 0
	v_mov_b64_e32 v[98:99], 0
	v_mov_b64_e32 v[100:101], 0
	v_mov_b64_e32 v[102:103], 0
	v_mov_b64_e32 v[104:105], 0
	v_mov_b64_e32 v[106:107], 0
	v_mov_b64_e32 v[108:109], 0
	v_mov_b64_e32 v[110:111], 0
	v_mov_b64_e32 v[112:113], 0
	v_mov_b64_e32 v[114:115], 0
	v_mov_b64_e32 v[116:117], 0
	v_mov_b64_e32 v[118:119], 0
	v_mov_b64_e32 v[120:121], 0
	v_mov_b64_e32 v[122:123], 0
	v_mov_b64_e32 v[124:125], 0
	v_mov_b64_e32 v[126:127], 0

.LBB0_630:
	s_mov_b32 s29, s15
	s_lshl_b64 s[30:31], s[28:29], 1
	s_add_u32 s30, s60, s30
	s_addc_u32 s31, s61, s31
	s_and_b64 s[36:37], exec, s[10:11]
	s_cselect_b32 s17, s31, s9
	s_cselect_b32 s29, s30, s8
	s_lshl_b64 s[34:35], s[34:35], 1
	s_add_u32 s34, s46, s34
	s_addc_u32 s35, s47, s35
	s_and_b64 s[10:11], exec, s[10:11]
	s_cselect_b32 s38, s35, s7
	s_cselect_b32 s39, s34, s6
	s_add_u32 s40, s6, 0x80000
	s_addc_u32 s41, s7, 0
	s_add_u32 s6, s8, 0x404000
	v_mov_b32_e32 v56, 0
	s_addc_u32 s7, s9, 0
	s_mov_b32 s42, -2
	v_mov_b64_e32 v[0:1], 0
	v_mov_b64_e32 v[2:3], 0
	v_mov_b64_e32 v[4:5], 0
	v_mov_b64_e32 v[6:7], 0
	v_mov_b64_e32 v[8:9], 0
	v_mov_b64_e32 v[10:11], 0
	v_mov_b64_e32 v[12:13], 0
	v_mov_b64_e32 v[14:15], 0
	v_mov_b64_e32 v[16:17], 0
	v_mov_b64_e32 v[18:19], 0
	v_mov_b64_e32 v[20:21], 0
	v_mov_b64_e32 v[22:23], 0
	v_mov_b64_e32 v[24:25], 0
	v_mov_b64_e32 v[26:27], 0
	v_mov_b64_e32 v[28:29], 0
	v_mov_b64_e32 v[30:31], 0
	v_mov_b64_e32 v[32:33], 0
	v_mov_b64_e32 v[34:35], 0
	v_mov_b64_e32 v[36:37], 0
	v_mov_b64_e32 v[38:39], 0
	v_mov_b64_e32 v[40:41], 0
	v_mov_b64_e32 v[42:43], 0
	v_mov_b64_e32 v[44:45], 0
	v_mov_b64_e32 v[46:47], 0
	v_mov_b64_e32 v[48:49], 0
	v_mov_b64_e32 v[50:51], 0
	v_mov_b64_e32 v[52:53], 0
	v_mov_b64_e32 v[54:55], 0
	v_mov_b32_e32 v57, 0
	v_mov_b64_e32 v[58:59], 0
	v_mov_b64_e32 v[60:61], 0
	v_mov_b64_e32 v[62:63], 0
	v_mov_b64_e32 v[64:65], 0
	v_mov_b64_e32 v[66:67], 0
	v_mov_b64_e32 v[68:69], 0
	v_mov_b64_e32 v[70:71], 0
	v_mov_b64_e32 v[72:73], 0
	v_mov_b64_e32 v[74:75], 0
	v_mov_b64_e32 v[76:77], 0
	v_mov_b64_e32 v[78:79], 0
	v_mov_b64_e32 v[80:81], 0
	v_mov_b64_e32 v[82:83], 0
	v_mov_b64_e32 v[84:85], 0
	v_mov_b64_e32 v[86:87], 0
	v_mov_b64_e32 v[88:89], 0
	v_mov_b64_e32 v[90:91], 0
	v_mov_b64_e32 v[92:93], 0
	v_mov_b64_e32 v[94:95], 0
	v_mov_b64_e32 v[96:97], 0
	v_mov_b64_e32 v[98:99], 0
	v_mov_b64_e32 v[100:101], 0
	v_mov_b64_e32 v[102:103], 0
	v_mov_b64_e32 v[104:105], 0
	v_mov_b64_e32 v[106:107], 0
	v_mov_b64_e32 v[108:109], 0
	v_mov_b64_e32 v[110:111], 0
	v_mov_b64_e32 v[112:113], 0
	v_mov_b64_e32 v[114:115], 0
	v_mov_b64_e32 v[116:117], 0
	v_mov_b64_e32 v[118:119], 0
	v_mov_b64_e32 v[120:121], 0
	v_mov_b64_e32 v[122:123], 0
	v_mov_b64_e32 v[124:125], 0
	v_mov_b64_e32 v[126:127], 0

.LBB0_731:
	s_mov_b32 s17, s9
	s_lshl_b64 s[20:21], s[16:17], 1
	s_add_u32 s20, s58, s20
	s_addc_u32 s21, s59, s21
	s_and_b64 s[22:23], s[6:7], exec
	s_mov_b32 s19, s9
	s_cselect_b32 s17, s21, s27
	s_cselect_b32 s54, s20, s26
	s_lshl_b64 s[22:23], s[18:19], 1
	s_add_u32 s22, s72, s22
	s_addc_u32 s23, s73, s23
	s_and_b64 s[28:29], s[6:7], exec
	s_cselect_b32 s19, s23, s25
	s_cselect_b32 s55, s22, s24
	s_add_u32 s56, s24, 0x1b0000
	s_addc_u32 s74, s25, 0
	s_add_u32 s24, s26, 0x404000
	v_mov_b32_e32 v32, 0
	s_addc_u32 s25, s27, 0
	s_mov_b32 s75, -2
	v_mov_b64_e32 v[0:1], 0
	v_mov_b64_e32 v[2:3], 0
	v_mov_b64_e32 v[4:5], 0
	v_mov_b64_e32 v[6:7], 0
	v_mov_b64_e32 v[8:9], 0
	v_mov_b64_e32 v[10:11], 0
	v_mov_b64_e32 v[12:13], 0
	v_mov_b64_e32 v[14:15], 0
	v_mov_b64_e32 v[16:17], 0
	v_mov_b64_e32 v[18:19], 0
	v_mov_b64_e32 v[20:21], 0
	v_mov_b64_e32 v[22:23], 0
	v_mov_b64_e32 v[24:25], 0
	v_mov_b64_e32 v[26:27], 0
	v_mov_b64_e32 v[28:29], 0
	v_mov_b64_e32 v[30:31], 0
	v_mov_b32_e32 v33, 0
	v_mov_b64_e32 v[34:35], 0
	v_mov_b64_e32 v[36:37], 0
	v_mov_b64_e32 v[38:39], 0
	v_mov_b64_e32 v[40:41], 0
	v_mov_b64_e32 v[42:43], 0
	v_mov_b64_e32 v[44:45], 0
	v_mov_b64_e32 v[46:47], 0
	v_mov_b64_e32 v[48:49], 0
	v_mov_b64_e32 v[50:51], 0
	v_mov_b64_e32 v[52:53], 0
	v_mov_b64_e32 v[54:55], 0
	v_mov_b64_e32 v[56:57], 0
	v_mov_b64_e32 v[58:59], 0
	v_mov_b64_e32 v[60:61], 0
	v_mov_b64_e32 v[62:63], 0
	v_mov_b64_e32 v[64:65], 0
	v_mov_b64_e32 v[66:67], 0
	v_mov_b64_e32 v[68:69], 0
	v_mov_b64_e32 v[70:71], 0
	v_mov_b64_e32 v[72:73], 0
	v_mov_b64_e32 v[74:75], 0
	v_mov_b64_e32 v[76:77], 0
	v_mov_b64_e32 v[78:79], 0
	v_mov_b64_e32 v[80:81], 0
	v_mov_b64_e32 v[82:83], 0
	v_mov_b64_e32 v[84:85], 0
	v_mov_b64_e32 v[86:87], 0
	v_mov_b64_e32 v[88:89], 0
	v_mov_b64_e32 v[90:91], 0
	v_mov_b64_e32 v[92:93], 0
	v_mov_b64_e32 v[94:95], 0
	v_mov_b64_e32 v[96:97], 0
	v_mov_b64_e32 v[98:99], 0
	v_mov_b64_e32 v[100:101], 0
	v_mov_b64_e32 v[102:103], 0
	v_mov_b64_e32 v[104:105], 0
	v_mov_b64_e32 v[106:107], 0
	v_mov_b64_e32 v[108:109], 0
	v_mov_b64_e32 v[110:111], 0
	v_mov_b64_e32 v[112:113], 0
	v_mov_b64_e32 v[114:115], 0
	v_mov_b64_e32 v[116:117], 0
	v_mov_b64_e32 v[118:119], 0
	v_mov_b64_e32 v[120:121], 0
	v_mov_b64_e32 v[122:123], 0
	v_mov_b64_e32 v[124:125], 0
	v_mov_b64_e32 v[126:127], 0

.LBB0_745:
	v_and_b32_e32 v141, 15, v11
	v_bfe_u32 v140, v11, 4, 2
	v_lshlrev_b32_e32 v15, 6, v141
	v_lshlrev_b32_e32 v11, 2, v11
	s_and_b32 s22, s4, 3
	v_lshl_or_b32 v15, v140, 4, v15
	s_lshl_b32 s10, s2, 13
	v_and_b32_e32 v11, 32, v11
	v_bitop3_b32 v16, v15, s10, v11 bitop3:0xde
	s_lshl_b32 s10, s22, 12
	v_bitop3_b32 v11, v15, s10, v11 bitop3:0xde
	s_mov_b64 s[10:11], 0x80
	s_add_i32 m0, s21, 0x18000
	v_lshl_add_u64 v[6:7], v[6:7], 0, s[10:11]
	s_waitcnt vmcnt(2)
	s_barrier
	global_load_lds_dwordx4 v[6:7], off
	v_lshl_add_u64 v[4:5], v[4:5], 0, s[10:11]
	s_add_i32 m0, s21, 0x1a000
	s_add_i32 s26, s21, 0x8000
	s_add_i32 s27, s21, 0xa000
	global_load_lds_dwordx4 v[4:5], off
	v_lshl_add_u64 v[2:3], v[2:3], 0, s[10:11]
	s_mov_b32 m0, s26
	s_add_u32 s18, s6, 0x80080
	global_load_lds_dwordx4 v[2:3], off
	v_lshl_add_u64 v[0:1], v[0:1], 0, s[10:11]
	s_mov_b32 m0, s27
	s_addc_u32 s19, s7, 0
	global_load_lds_dwordx4 v[0:1], off
	s_add_i32 m0, s21, 0x1c000
	s_nop 0
	global_load_lds_dwordx4 v132, s[18:19]
	s_add_i32 m0, s21, 0x1e000
	s_lshl_b32 s12, s12, 17
	global_load_lds_dwordx4 v128, s[18:19]
	v_lshlrev_b32_e32 v0, 15, v12
	s_and_b32 s12, s12, 0x300000
	v_and_b32_e32 v0, 0xffff0000, v0
	s_add_u32 s12, s48, s12
	v_lshl_add_u32 v0, v13, 12, v0
	v_and_b32_e32 v1, 1, v12
	s_addc_u32 s13, s49, 0
	v_lshl_or_b32 v0, v1, 6, v0
	s_add_i32 s15, s15, s17
	v_lshl_add_u32 v0, v14, 1, v0
	v_mov_b32_e32 v1, v133
	s_lshl_b32 s15, s15, 18
	v_lshl_add_u64 v[0:1], s[12:13], 0, v[0:1]
	s_mov_b64 s[18:19], 0x21080080
	s_and_b32 s15, s15, 0x1f00000
	v_lshl_add_u64 v[136:137], v[0:1], 0, s[18:19]
	v_lshlrev_b32_e32 v0, 15, v8
	s_add_u32 s14, s14, s15
	v_and_b32_e32 v0, 0xffff0000, v0
	s_addc_u32 s15, 0, 0
	v_lshl_add_u32 v0, v9, 12, v0
	v_and_b32_e32 v1, 1, v8
	s_add_u32 s14, s48, s14
	v_lshl_or_b32 v0, v1, 6, v0
	s_addc_u32 s15, s49, s15
	s_waitcnt vmcnt(6)
	v_lshl_add_u32 v0, v10, 1, v0
	v_mov_b32_e32 v1, v133
	s_add_u32 s28, s14, 0x16000100
	v_lshl_add_u64 v[0:1], s[12:13], 0, v[0:1]
	s_addc_u32 s29, s15, 0
	s_add_i32 s34, s57, s16
	s_add_i32 s36, s81, s16
	s_add_i32 s38, s82, s16
	s_add_i32 s40, s83, s16
	v_lshl_add_u64 v[138:139], v[0:1], 0, s[18:19]
	s_mov_b32 s30, -2
	s_mov_b64 s[14:15], 0
	v_add_u32_e32 v142, s57, v11
	v_add_u32_e32 v143, s81, v11
	v_add_u32_e32 v144, 0, v16
	s_add_i32 s31, s21, 0xc000
	s_add_i32 s33, s21, 0xe000
	s_add_i32 s35, s34, 0x2000
	s_add_i32 s37, s36, 0x2000
	v_add_u32_e32 v145, s82, v11
	v_add_u32_e32 v146, s83, v11
	s_add_i32 s39, s38, 0x2000
	s_add_i32 s41, s40, 0x2000
	v_mov_b64_e32 v[0:1], 0
	v_mov_b64_e32 v[2:3], 0
	v_mov_b64_e32 v[4:5], 0
	v_mov_b64_e32 v[6:7], 0
	v_mov_b64_e32 v[8:9], 0
	v_mov_b64_e32 v[10:11], 0
	v_mov_b64_e32 v[12:13], 0
	v_mov_b64_e32 v[14:15], 0
	v_mov_b64_e32 v[16:17], 0
	v_mov_b64_e32 v[18:19], 0
	v_mov_b64_e32 v[20:21], 0
	v_mov_b64_e32 v[22:23], 0
	v_mov_b64_e32 v[24:25], 0
	v_mov_b64_e32 v[26:27], 0
	v_mov_b64_e32 v[28:29], 0
	v_mov_b64_e32 v[30:31], 0
	v_mov_b64_e32 v[32:33], 0
	v_mov_b64_e32 v[34:35], 0
	v_mov_b64_e32 v[36:37], 0
	v_mov_b64_e32 v[38:39], 0
	v_mov_b64_e32 v[40:41], 0
	v_mov_b64_e32 v[42:43], 0
	v_mov_b64_e32 v[44:45], 0
	v_mov_b64_e32 v[46:47], 0
	v_mov_b64_e32 v[48:49], 0
	v_mov_b64_e32 v[50:51], 0
	v_mov_b64_e32 v[52:53], 0
	v_mov_b64_e32 v[54:55], 0
	v_mov_b64_e32 v[56:57], 0
	v_mov_b64_e32 v[58:59], 0
	v_mov_b64_e32 v[60:61], 0
	v_mov_b64_e32 v[62:63], 0
	v_mov_b64_e32 v[64:65], 0
	v_mov_b64_e32 v[66:67], 0
	v_mov_b64_e32 v[68:69], 0
	v_mov_b64_e32 v[70:71], 0
	v_mov_b64_e32 v[72:73], 0
	v_mov_b64_e32 v[74:75], 0
	v_mov_b64_e32 v[76:77], 0
	v_mov_b64_e32 v[78:79], 0
	v_mov_b64_e32 v[80:81], 0
	v_mov_b64_e32 v[82:83], 0
	v_mov_b64_e32 v[84:85], 0
	v_mov_b64_e32 v[86:87], 0
	v_mov_b64_e32 v[88:89], 0
	v_mov_b64_e32 v[90:91], 0
	v_mov_b64_e32 v[92:93], 0
	v_mov_b64_e32 v[94:95], 0
	v_mov_b64_e32 v[96:97], 0
	v_mov_b64_e32 v[98:99], 0
	v_mov_b64_e32 v[100:101], 0
	v_mov_b64_e32 v[102:103], 0
	v_mov_b64_e32 v[104:105], 0
	v_mov_b64_e32 v[106:107], 0
	v_mov_b64_e32 v[108:109], 0
	v_mov_b64_e32 v[110:111], 0
	v_mov_b64_e32 v[112:113], 0
	v_mov_b64_e32 v[114:115], 0
	v_mov_b64_e32 v[116:117], 0
	v_mov_b64_e32 v[118:119], 0
	v_mov_b64_e32 v[120:121], 0
	v_mov_b64_e32 v[122:123], 0
	v_mov_b64_e32 v[124:125], 0
	v_mov_b64_e32 v[126:127], 0
	s_barrier

.LBB0_895:
	v_and_b32_e32 v141, 15, v11
	v_bfe_u32 v140, v11, 4, 2
	v_lshlrev_b32_e32 v15, 6, v141
	v_lshlrev_b32_e32 v11, 2, v11
	s_and_b32 s22, s3, 3
	v_lshl_or_b32 v15, v140, 4, v15
	s_lshl_b32 s10, s2, 13
	v_and_b32_e32 v11, 32, v11
	v_bitop3_b32 v16, v15, s10, v11 bitop3:0xde
	s_lshl_b32 s10, s22, 12
	v_bitop3_b32 v11, v15, s10, v11 bitop3:0xde
	s_mov_b64 s[10:11], 0x80
	s_add_i32 m0, s21, 0x18000
	v_lshl_add_u64 v[6:7], v[6:7], 0, s[10:11]
	s_waitcnt vmcnt(2)
	s_barrier
	global_load_lds_dwordx4 v[6:7], off
	v_lshl_add_u64 v[4:5], v[4:5], 0, s[10:11]
	s_add_i32 m0, s21, 0x1a000
	s_add_i32 s26, s21, 0x8000
	s_add_i32 s27, s21, 0xa000
	global_load_lds_dwordx4 v[4:5], off
	v_lshl_add_u64 v[2:3], v[2:3], 0, s[10:11]
	s_mov_b32 m0, s26
	s_add_u32 s18, s6, 0x80080
	global_load_lds_dwordx4 v[2:3], off
	v_lshl_add_u64 v[0:1], v[0:1], 0, s[10:11]
	s_mov_b32 m0, s27
	s_addc_u32 s19, s7, 0
	global_load_lds_dwordx4 v[0:1], off
	s_add_i32 m0, s21, 0x1c000
	s_nop 0
	global_load_lds_dwordx4 v132, s[18:19]
	s_add_i32 m0, s21, 0x1e000
	s_add_i32 s12, s17, s14
	global_load_lds_dwordx4 v128, s[18:19]
	v_lshlrev_b32_e32 v0, 16, v12
	v_and_b32_e32 v0, 0xfffe0000, v0
	s_lshl_b64 s[12:13], s[12:13], 1
	v_lshl_add_u32 v0, v13, 13, v0
	v_and_b32_e32 v1, 1, v12
	s_add_u32 s12, s48, s12
	v_lshl_or_b32 v0, v1, 6, v0
	s_addc_u32 s13, s49, s13
	v_lshl_add_u32 v0, v14, 1, v0
	v_mov_b32_e32 v1, v133
	v_lshl_add_u64 v[0:1], s[12:13], 0, v[0:1]
	s_mov_b64 s[18:19], 0x21500080
	v_lshl_add_u64 v[136:137], v[0:1], 0, s[18:19]
	v_lshlrev_b32_e32 v0, 16, v8
	s_add_i32 s15, s15, s14
	v_and_b32_e32 v0, 0xfffe0000, v0
	s_lshl_b32 s14, s15, 1
	v_lshl_add_u32 v0, v9, 13, v0
	v_and_b32_e32 v1, 1, v8
	s_add_u32 s14, s48, s14
	v_lshl_or_b32 v0, v1, 6, v0
	s_addc_u32 s15, s49, 0
	s_waitcnt vmcnt(6)
	v_lshl_add_u32 v0, v10, 1, v0
	v_mov_b32_e32 v1, v133
	s_add_u32 s28, s14, 0x15000100
	v_lshl_add_u64 v[0:1], s[12:13], 0, v[0:1]
	s_addc_u32 s29, s15, 0
	s_add_i32 s34, s57, s16
	s_add_i32 s36, s81, s16
	s_add_i32 s38, s82, s16
	s_add_i32 s40, s83, s16
	v_lshl_add_u64 v[138:139], v[0:1], 0, s[18:19]
	s_mov_b32 s30, -2
	s_mov_b64 s[14:15], 0
	v_add_u32_e32 v142, s57, v11
	v_add_u32_e32 v143, s81, v11
	v_add_u32_e32 v144, 0, v16
	s_add_i32 s31, s21, 0xc000
	s_add_i32 s33, s21, 0xe000
	s_add_i32 s35, s34, 0x2000
	s_add_i32 s37, s36, 0x2000
	v_add_u32_e32 v145, s82, v11
	v_add_u32_e32 v146, s83, v11
	s_add_i32 s39, s38, 0x2000
	s_add_i32 s41, s40, 0x2000
	v_mov_b64_e32 v[0:1], 0
	v_mov_b64_e32 v[2:3], 0
	v_mov_b64_e32 v[4:5], 0
	v_mov_b64_e32 v[6:7], 0
	v_mov_b64_e32 v[8:9], 0
	v_mov_b64_e32 v[10:11], 0
	v_mov_b64_e32 v[12:13], 0
	v_mov_b64_e32 v[14:15], 0
	v_mov_b64_e32 v[16:17], 0
	v_mov_b64_e32 v[18:19], 0
	v_mov_b64_e32 v[20:21], 0
	v_mov_b64_e32 v[22:23], 0
	v_mov_b64_e32 v[24:25], 0
	v_mov_b64_e32 v[26:27], 0
	v_mov_b64_e32 v[28:29], 0
	v_mov_b64_e32 v[30:31], 0
	v_mov_b64_e32 v[32:33], 0
	v_mov_b64_e32 v[34:35], 0
	v_mov_b64_e32 v[36:37], 0
	v_mov_b64_e32 v[38:39], 0
	v_mov_b64_e32 v[40:41], 0
	v_mov_b64_e32 v[42:43], 0
	v_mov_b64_e32 v[44:45], 0
	v_mov_b64_e32 v[46:47], 0
	v_mov_b64_e32 v[48:49], 0
	v_mov_b64_e32 v[50:51], 0
	v_mov_b64_e32 v[52:53], 0
	v_mov_b64_e32 v[54:55], 0
	v_mov_b64_e32 v[56:57], 0
	v_mov_b64_e32 v[58:59], 0
	v_mov_b64_e32 v[60:61], 0
	v_mov_b64_e32 v[62:63], 0
	v_mov_b64_e32 v[64:65], 0
	v_mov_b64_e32 v[66:67], 0
	v_mov_b64_e32 v[68:69], 0
	v_mov_b64_e32 v[70:71], 0
	v_mov_b64_e32 v[72:73], 0
	v_mov_b64_e32 v[74:75], 0
	v_mov_b64_e32 v[76:77], 0
	v_mov_b64_e32 v[78:79], 0
	v_mov_b64_e32 v[80:81], 0
	v_mov_b64_e32 v[82:83], 0
	v_mov_b64_e32 v[84:85], 0
	v_mov_b64_e32 v[86:87], 0
	v_mov_b64_e32 v[88:89], 0
	v_mov_b64_e32 v[90:91], 0
	v_mov_b64_e32 v[92:93], 0
	v_mov_b64_e32 v[94:95], 0
	v_mov_b64_e32 v[96:97], 0
	v_mov_b64_e32 v[98:99], 0
	v_mov_b64_e32 v[100:101], 0
	v_mov_b64_e32 v[102:103], 0
	v_mov_b64_e32 v[104:105], 0
	v_mov_b64_e32 v[106:107], 0
	v_mov_b64_e32 v[108:109], 0
	v_mov_b64_e32 v[110:111], 0
	v_mov_b64_e32 v[112:113], 0
	v_mov_b64_e32 v[114:115], 0
	v_mov_b64_e32 v[116:117], 0
	v_mov_b64_e32 v[118:119], 0
	v_mov_b64_e32 v[120:121], 0
	v_mov_b64_e32 v[122:123], 0
	v_mov_b64_e32 v[124:125], 0
	v_mov_b64_e32 v[126:127], 0
	s_barrier

.LBB0_903:
	v_and_b32_e32 v141, 15, v7
	v_bfe_u32 v140, v7, 4, 2
	v_lshlrev_b32_e32 v11, 6, v141
	v_lshlrev_b32_e32 v7, 2, v7
	s_and_b32 s22, s3, 3
	v_lshl_or_b32 v11, v140, 4, v11
	s_lshl_b32 s10, s2, 13
	v_and_b32_e32 v7, 32, v7
	v_bitop3_b32 v14, v11, s10, v7 bitop3:0xde
	s_lshl_b32 s10, s22, 12
	v_bitop3_b32 v7, v11, s10, v7 bitop3:0xde
	s_add_u32 s10, s12, 0x1080
	s_addc_u32 s11, s13, 0
	s_add_i32 m0, s21, 0x18000
	s_waitcnt vmcnt(2)
	s_barrier
	global_load_lds_dwordx4 v132, s[10:11]
	v_lshl_add_u64 v[12:13], s[10:11], 0, v[128:129]
	s_add_i32 m0, s21, 0x1a000
	s_mov_b64 s[10:11], 0x80
	s_add_i32 s26, s21, 0x8000
	s_add_i32 s27, s21, 0xa000
	global_load_lds_dwordx4 v[12:13], off
	v_lshl_add_u64 v[2:3], v[2:3], 0, s[10:11]
	s_mov_b32 m0, s26
	s_add_u32 s12, s12, 0x101080
	global_load_lds_dwordx4 v[2:3], off
	v_lshl_add_u64 v[0:1], v[0:1], 0, s[10:11]
	s_mov_b32 m0, s27
	s_addc_u32 s13, s13, 0
	global_load_lds_dwordx4 v[0:1], off
	s_add_i32 m0, s21, 0x1c000
	s_nop 0
	global_load_lds_dwordx4 v132, s[12:13]
	v_lshl_add_u64 v[0:1], s[12:13], 0, v[128:129]
	s_add_i32 m0, s21, 0x1e000
	s_add_i32 s12, s5, s20
	global_load_lds_dwordx4 v[0:1], off
	v_lshlrev_b32_e32 v0, 15, v8
	v_and_b32_e32 v0, 0xffff0000, v0
	s_lshl_b32 s12, s12, 1
	v_lshl_add_u32 v0, v9, 12, v0
	v_and_b32_e32 v1, 1, v8
	s_add_u32 s12, s48, s12
	v_lshl_or_b32 v0, v1, 6, v0
	s_addc_u32 s13, s49, 0
	v_lshl_add_u32 v0, v10, 1, v0
	v_mov_b32_e32 v1, v133
	v_lshl_add_u64 v[0:1], s[12:13], 0, v[0:1]
	s_mov_b64 s[18:19], 0x18080080
	v_lshl_add_u64 v[136:137], v[0:1], 0, s[18:19]
	v_lshlrev_b32_e32 v0, 15, v4
	s_add_i32 s14, s17, s20
	v_and_b32_e32 v0, 0xffff0000, v0
	s_lshl_b64 s[14:15], s[14:15], 1
	v_lshl_add_u32 v0, v5, 12, v0
	v_and_b32_e32 v1, 1, v4
	s_add_u32 s14, s48, s14
	v_lshl_or_b32 v0, v1, 6, v0
	s_addc_u32 s15, s49, s15
	s_waitcnt vmcnt(6)
	v_lshl_add_u32 v0, v6, 1, v0
	v_mov_b32_e32 v1, v133
	s_add_u32 s28, s14, 0x21401100
	v_lshl_add_u64 v[0:1], s[12:13], 0, v[0:1]
	s_addc_u32 s29, s15, 0
	s_add_i32 s34, s57, s16
	s_add_i32 s36, s81, s16
	s_add_i32 s38, s82, s16
	s_add_i32 s40, s83, s16
	v_lshl_add_u64 v[138:139], v[0:1], 0, s[18:19]
	s_mov_b32 s30, -2
	s_mov_b64 s[14:15], 0
	v_add_u32_e32 v142, s57, v7
	v_add_u32_e32 v143, s81, v7
	v_add_u32_e32 v144, 0, v14
	s_add_i32 s31, s21, 0xc000
	s_add_i32 s33, s21, 0xe000
	s_add_i32 s35, s34, 0x2000
	s_add_i32 s37, s36, 0x2000
	v_add_u32_e32 v145, s82, v7
	v_add_u32_e32 v146, s83, v7
	s_add_i32 s39, s38, 0x2000
	s_add_i32 s41, s40, 0x2000
	v_mov_b64_e32 v[0:1], 0
	v_mov_b64_e32 v[2:3], 0
	v_mov_b64_e32 v[4:5], 0
	v_mov_b64_e32 v[6:7], 0
	v_mov_b64_e32 v[8:9], 0
	v_mov_b64_e32 v[10:11], 0
	v_mov_b64_e32 v[12:13], 0
	v_mov_b64_e32 v[14:15], 0
	v_mov_b64_e32 v[16:17], 0
	v_mov_b64_e32 v[18:19], 0
	v_mov_b64_e32 v[20:21], 0
	v_mov_b64_e32 v[22:23], 0
	v_mov_b64_e32 v[24:25], 0
	v_mov_b64_e32 v[26:27], 0
	v_mov_b64_e32 v[28:29], 0
	v_mov_b64_e32 v[30:31], 0
	v_mov_b64_e32 v[32:33], 0
	v_mov_b64_e32 v[34:35], 0
	v_mov_b64_e32 v[36:37], 0
	v_mov_b64_e32 v[38:39], 0
	v_mov_b64_e32 v[40:41], 0
	v_mov_b64_e32 v[42:43], 0
	v_mov_b64_e32 v[44:45], 0
	v_mov_b64_e32 v[46:47], 0
	v_mov_b64_e32 v[48:49], 0
	v_mov_b64_e32 v[50:51], 0
	v_mov_b64_e32 v[52:53], 0
	v_mov_b64_e32 v[54:55], 0
	v_mov_b64_e32 v[56:57], 0
	v_mov_b64_e32 v[58:59], 0
	v_mov_b64_e32 v[60:61], 0
	v_mov_b64_e32 v[62:63], 0
	v_mov_b64_e32 v[64:65], 0
	v_mov_b64_e32 v[66:67], 0
	v_mov_b64_e32 v[68:69], 0
	v_mov_b64_e32 v[70:71], 0
	v_mov_b64_e32 v[72:73], 0
	v_mov_b64_e32 v[74:75], 0
	v_mov_b64_e32 v[76:77], 0
	v_mov_b64_e32 v[78:79], 0
	v_mov_b64_e32 v[80:81], 0
	v_mov_b64_e32 v[82:83], 0
	v_mov_b64_e32 v[84:85], 0
	v_mov_b64_e32 v[86:87], 0
	v_mov_b64_e32 v[88:89], 0
	v_mov_b64_e32 v[90:91], 0
	v_mov_b64_e32 v[92:93], 0
	v_mov_b64_e32 v[94:95], 0
	v_mov_b64_e32 v[96:97], 0
	v_mov_b64_e32 v[98:99], 0
	v_mov_b64_e32 v[100:101], 0
	v_mov_b64_e32 v[102:103], 0
	v_mov_b64_e32 v[104:105], 0
	v_mov_b64_e32 v[106:107], 0
	v_mov_b64_e32 v[108:109], 0
	v_mov_b64_e32 v[110:111], 0
	v_mov_b64_e32 v[112:113], 0
	v_mov_b64_e32 v[114:115], 0
	v_mov_b64_e32 v[116:117], 0
	v_mov_b64_e32 v[118:119], 0
	v_mov_b64_e32 v[120:121], 0
	v_mov_b64_e32 v[122:123], 0
	v_mov_b64_e32 v[124:125], 0
	v_mov_b64_e32 v[126:127], 0
	s_barrier

.LBB0_1281:
	s_mov_b32 s31, s13
	s_lshl_b64 s[34:35], s[30:31], 1
	s_add_u32 s34, s64, s34
	s_addc_u32 s35, s65, s35
	s_and_b64 s[38:39], exec, s[10:11]
	s_cselect_b32 s12, s35, s9
	s_cselect_b32 s15, s34, s8
	s_lshl_b64 s[36:37], s[36:37], 1
	s_add_u32 s36, s91, s36
	s_addc_u32 s37, s92, s37
	s_and_b64 s[10:11], exec, s[10:11]
	s_cselect_b32 s31, s37, s7
	s_cselect_b32 s41, s36, s6
	s_add_u32 s42, s6, 0x80000
	s_addc_u32 s43, s7, 0
	s_add_u32 s6, s8, 0x404000
	v_mov_b32_e32 v56, 0
	s_addc_u32 s7, s9, 0
	s_mov_b32 s44, -2
	v_mov_b64_e32 v[0:1], 0
	v_mov_b64_e32 v[2:3], 0
	v_mov_b64_e32 v[4:5], 0
	v_mov_b64_e32 v[6:7], 0
	v_mov_b64_e32 v[8:9], 0
	v_mov_b64_e32 v[10:11], 0
	v_mov_b64_e32 v[12:13], 0
	v_mov_b64_e32 v[14:15], 0
	v_mov_b64_e32 v[16:17], 0
	v_mov_b64_e32 v[18:19], 0
	v_mov_b64_e32 v[20:21], 0
	v_mov_b64_e32 v[22:23], 0
	v_mov_b64_e32 v[24:25], 0
	v_mov_b64_e32 v[26:27], 0
	v_mov_b64_e32 v[28:29], 0
	v_mov_b64_e32 v[30:31], 0
	v_mov_b64_e32 v[32:33], 0
	v_mov_b64_e32 v[34:35], 0
	v_mov_b64_e32 v[36:37], 0
	v_mov_b64_e32 v[38:39], 0
	v_mov_b64_e32 v[40:41], 0
	v_mov_b64_e32 v[42:43], 0
	v_mov_b64_e32 v[44:45], 0
	v_mov_b64_e32 v[46:47], 0
	v_mov_b64_e32 v[48:49], 0
	v_mov_b64_e32 v[50:51], 0
	v_mov_b64_e32 v[52:53], 0
	v_mov_b64_e32 v[54:55], 0
	v_mov_b32_e32 v57, 0
	v_mov_b64_e32 v[58:59], 0
	v_mov_b64_e32 v[60:61], 0
	v_mov_b64_e32 v[62:63], 0
	v_mov_b64_e32 v[64:65], 0
	v_mov_b64_e32 v[66:67], 0
	v_mov_b64_e32 v[68:69], 0
	v_mov_b64_e32 v[70:71], 0
	v_mov_b64_e32 v[72:73], 0
	v_mov_b64_e32 v[74:75], 0
	v_mov_b64_e32 v[76:77], 0
	v_mov_b64_e32 v[78:79], 0
	v_mov_b64_e32 v[80:81], 0
	v_mov_b64_e32 v[82:83], 0
	v_mov_b64_e32 v[84:85], 0
	v_mov_b64_e32 v[86:87], 0
	v_mov_b64_e32 v[88:89], 0
	v_mov_b64_e32 v[90:91], 0
	v_mov_b64_e32 v[92:93], 0
	v_mov_b64_e32 v[94:95], 0
	v_mov_b64_e32 v[96:97], 0
	v_mov_b64_e32 v[98:99], 0
	v_mov_b64_e32 v[100:101], 0
	v_mov_b64_e32 v[102:103], 0
	v_mov_b64_e32 v[104:105], 0
	v_mov_b64_e32 v[106:107], 0
	v_mov_b64_e32 v[108:109], 0
	v_mov_b64_e32 v[110:111], 0
	v_mov_b64_e32 v[112:113], 0
	v_mov_b64_e32 v[114:115], 0
	v_mov_b64_e32 v[116:117], 0
	v_mov_b64_e32 v[118:119], 0
	v_mov_b64_e32 v[120:121], 0
	v_mov_b64_e32 v[122:123], 0
	v_mov_b64_e32 v[124:125], 0
	v_mov_b64_e32 v[126:127], 0

.LBB0_1403:
	s_mov_b32 s17, s9
	s_lshl_b64 s[20:21], s[16:17], 1
	s_add_u32 s20, s58, s20
	s_addc_u32 s21, s59, s21
	s_and_b64 s[22:23], s[6:7], exec
	s_mov_b32 s19, s9
	s_cselect_b32 s8, s21, s27
	s_cselect_b32 s17, s20, s26
	s_lshl_b64 s[22:23], s[18:19], 1
	v_readlane_b32 s19, v250, 17
	s_add_u32 s22, s19, s22
	v_readlane_b32 s19, v250, 4
	s_addc_u32 s23, s19, s23
	s_and_b64 s[28:29], s[6:7], exec
	s_cselect_b32 s19, s23, s25
	s_cselect_b32 s47, s22, s24
	s_add_u32 s50, s24, 0x100
	s_addc_u32 s51, s25, 0
	s_add_u32 s24, s26, 0x404000
	v_mov_b32_e32 v0, 0
	s_addc_u32 s25, s27, 0
	s_mov_b32 s52, -2
	v_mov_b32_e32 v1, 0
	v_mov_b64_e32 v[2:3], 0
	v_mov_b64_e32 v[4:5], 0
	v_mov_b64_e32 v[6:7], 0
	v_mov_b64_e32 v[8:9], 0
	v_mov_b64_e32 v[10:11], 0
	v_mov_b64_e32 v[12:13], 0
	v_mov_b64_e32 v[14:15], 0
	v_mov_b64_e32 v[16:17], 0
	v_mov_b64_e32 v[18:19], 0
	v_mov_b64_e32 v[20:21], 0
	v_mov_b64_e32 v[22:23], 0
	v_mov_b64_e32 v[24:25], 0
	v_mov_b64_e32 v[26:27], 0
	v_mov_b64_e32 v[28:29], 0
	v_mov_b64_e32 v[30:31], 0
	v_mov_b64_e32 v[32:33], 0
	v_mov_b64_e32 v[34:35], 0
	v_mov_b64_e32 v[36:37], 0
	v_mov_b64_e32 v[38:39], 0
	v_mov_b64_e32 v[40:41], 0
	v_mov_b64_e32 v[42:43], 0
	v_mov_b64_e32 v[44:45], 0
	v_mov_b64_e32 v[46:47], 0
	v_mov_b64_e32 v[48:49], 0
	v_mov_b64_e32 v[50:51], 0
	v_mov_b64_e32 v[52:53], 0
	v_mov_b64_e32 v[54:55], 0
	v_mov_b64_e32 v[56:57], 0
	v_mov_b64_e32 v[58:59], 0
	v_mov_b64_e32 v[60:61], 0
	v_mov_b64_e32 v[62:63], 0
	v_mov_b64_e32 v[64:65], 0
	v_mov_b64_e32 v[66:67], 0
	v_mov_b64_e32 v[68:69], 0
	v_mov_b64_e32 v[70:71], 0
	v_mov_b64_e32 v[72:73], 0
	v_mov_b64_e32 v[74:75], 0
	v_mov_b64_e32 v[76:77], 0
	v_mov_b64_e32 v[78:79], 0
	v_mov_b64_e32 v[80:81], 0
	v_mov_b64_e32 v[82:83], 0
	v_mov_b64_e32 v[84:85], 0
	v_mov_b64_e32 v[86:87], 0
	v_mov_b64_e32 v[88:89], 0
	v_mov_b64_e32 v[90:91], 0
	v_mov_b64_e32 v[92:93], 0
	v_mov_b64_e32 v[94:95], 0
	v_mov_b64_e32 v[96:97], 0
	v_mov_b64_e32 v[98:99], 0
	v_mov_b64_e32 v[100:101], 0
	v_mov_b64_e32 v[102:103], 0
	v_mov_b64_e32 v[104:105], 0
	v_mov_b64_e32 v[106:107], 0
	v_mov_b64_e32 v[108:109], 0
	v_mov_b64_e32 v[110:111], 0
	v_mov_b64_e32 v[112:113], 0
	v_mov_b64_e32 v[114:115], 0
	v_mov_b64_e32 v[116:117], 0
	v_mov_b64_e32 v[118:119], 0
	v_mov_b64_e32 v[120:121], 0
	v_mov_b64_e32 v[122:123], 0
	v_mov_b64_e32 v[124:125], 0
	v_mov_b64_e32 v[126:127], 0

.LBB0_1511:
	s_mov_b32 s29, s13
	s_lshl_b64 s[34:35], s[28:29], 1
	s_add_u32 s34, s91, s34
	s_addc_u32 s35, s92, s35
	s_and_b64 s[36:37], s[10:11], exec
	s_mov_b32 s31, s13
	s_cselect_b32 s12, s35, s9
	s_cselect_b32 s15, s34, s8
	s_lshl_b64 s[36:37], s[30:31], 1
	s_add_u32 s36, s84, s36
	s_addc_u32 s37, s85, s37
	s_and_b64 s[10:11], s[10:11], exec
	s_cselect_b32 s29, s37, s7
	s_cselect_b32 s31, s36, s6
	s_add_u32 s41, s6, 0x100
	s_addc_u32 s42, s7, 0
	s_add_u32 s6, s8, 0x404000
	v_mov_b32_e32 v56, 0
	s_addc_u32 s7, s9, 0
	s_mov_b32 s43, -2
	v_mov_b64_e32 v[0:1], 0
	v_mov_b64_e32 v[2:3], 0
	v_mov_b64_e32 v[4:5], 0
	v_mov_b64_e32 v[6:7], 0
	v_mov_b64_e32 v[8:9], 0
	v_mov_b64_e32 v[10:11], 0
	v_mov_b64_e32 v[12:13], 0
	v_mov_b64_e32 v[14:15], 0
	v_mov_b64_e32 v[16:17], 0
	v_mov_b64_e32 v[18:19], 0
	v_mov_b64_e32 v[20:21], 0
	v_mov_b64_e32 v[22:23], 0
	v_mov_b64_e32 v[24:25], 0
	v_mov_b64_e32 v[26:27], 0
	v_mov_b64_e32 v[28:29], 0
	v_mov_b64_e32 v[30:31], 0
	v_mov_b64_e32 v[32:33], 0
	v_mov_b64_e32 v[34:35], 0
	v_mov_b64_e32 v[36:37], 0
	v_mov_b64_e32 v[38:39], 0
	v_mov_b64_e32 v[40:41], 0
	v_mov_b64_e32 v[42:43], 0
	v_mov_b64_e32 v[44:45], 0
	v_mov_b64_e32 v[46:47], 0
	v_mov_b64_e32 v[48:49], 0
	v_mov_b64_e32 v[50:51], 0
	v_mov_b64_e32 v[52:53], 0
	v_mov_b64_e32 v[54:55], 0
	v_mov_b32_e32 v57, 0
	v_mov_b64_e32 v[58:59], 0
	v_mov_b64_e32 v[60:61], 0
	v_mov_b64_e32 v[62:63], 0
	v_mov_b64_e32 v[64:65], 0
	v_mov_b64_e32 v[66:67], 0
	v_mov_b64_e32 v[68:69], 0
	v_mov_b64_e32 v[70:71], 0
	v_mov_b64_e32 v[72:73], 0
	v_mov_b64_e32 v[74:75], 0
	v_mov_b64_e32 v[76:77], 0
	v_mov_b64_e32 v[78:79], 0
	v_mov_b64_e32 v[80:81], 0
	v_mov_b64_e32 v[82:83], 0
	v_mov_b64_e32 v[84:85], 0
	v_mov_b64_e32 v[86:87], 0
	v_mov_b64_e32 v[88:89], 0
	v_mov_b64_e32 v[90:91], 0
	v_mov_b64_e32 v[92:93], 0
	v_mov_b64_e32 v[94:95], 0
	v_mov_b64_e32 v[96:97], 0
	v_mov_b64_e32 v[98:99], 0
	v_mov_b64_e32 v[100:101], 0
	v_mov_b64_e32 v[102:103], 0
	v_mov_b64_e32 v[104:105], 0
	v_mov_b64_e32 v[106:107], 0
	v_mov_b64_e32 v[108:109], 0
	v_mov_b64_e32 v[110:111], 0
	v_mov_b64_e32 v[112:113], 0
	v_mov_b64_e32 v[114:115], 0
	v_mov_b64_e32 v[116:117], 0
	v_mov_b64_e32 v[118:119], 0
	v_mov_b64_e32 v[120:121], 0
	v_mov_b64_e32 v[122:123], 0
	v_mov_b64_e32 v[124:125], 0
	v_mov_b64_e32 v[126:127], 0

.LBB0_1627:
	s_mov_b32 s17, s9
	s_lshl_b64 s[20:21], s[16:17], 1
	s_add_u32 s20, s58, s20
	s_addc_u32 s21, s59, s21
	s_and_b64 s[22:23], s[6:7], exec
	s_mov_b32 s19, s9
	s_cselect_b32 s17, s21, s27
	s_cselect_b32 s46, s20, s26
	s_lshl_b64 s[22:23], s[18:19], 1
	s_add_u32 s22, s4, s22
	s_addc_u32 s23, s5, s23
	s_and_b64 s[28:29], s[6:7], exec
	s_cselect_b32 s19, s23, s25
	s_cselect_b32 s47, s22, s24
	s_add_u32 s50, s24, 0x2c0000
	s_addc_u32 s51, s25, 0
	s_add_u32 s24, s26, 0x404000
	v_mov_b32_e32 v0, 0
	s_addc_u32 s25, s27, 0
	s_mov_b32 s52, -2
	v_mov_b32_e32 v1, 0
	v_mov_b64_e32 v[2:3], 0
	v_mov_b64_e32 v[4:5], 0
	v_mov_b64_e32 v[6:7], 0
	v_mov_b64_e32 v[8:9], 0
	v_mov_b64_e32 v[10:11], 0
	v_mov_b64_e32 v[12:13], 0
	v_mov_b64_e32 v[14:15], 0
	v_mov_b64_e32 v[16:17], 0
	v_mov_b64_e32 v[18:19], 0
	v_mov_b64_e32 v[20:21], 0
	v_mov_b64_e32 v[22:23], 0
	v_mov_b64_e32 v[24:25], 0
	v_mov_b64_e32 v[26:27], 0
	v_mov_b64_e32 v[28:29], 0
	v_mov_b64_e32 v[30:31], 0
	v_mov_b64_e32 v[32:33], 0
	v_mov_b64_e32 v[34:35], 0
	v_mov_b64_e32 v[36:37], 0
	v_mov_b64_e32 v[38:39], 0
	v_mov_b64_e32 v[40:41], 0
	v_mov_b64_e32 v[42:43], 0
	v_mov_b64_e32 v[44:45], 0
	v_mov_b64_e32 v[46:47], 0
	v_mov_b64_e32 v[48:49], 0
	v_mov_b64_e32 v[50:51], 0
	v_mov_b64_e32 v[52:53], 0
	v_mov_b64_e32 v[54:55], 0
	v_mov_b64_e32 v[56:57], 0
	v_mov_b64_e32 v[58:59], 0
	v_mov_b64_e32 v[60:61], 0
	v_mov_b64_e32 v[62:63], 0
	v_mov_b64_e32 v[64:65], 0
	v_mov_b64_e32 v[66:67], 0
	v_mov_b64_e32 v[68:69], 0
	v_mov_b64_e32 v[70:71], 0
	v_mov_b64_e32 v[72:73], 0
	v_mov_b64_e32 v[74:75], 0
	v_mov_b64_e32 v[76:77], 0
	v_mov_b64_e32 v[78:79], 0
	v_mov_b64_e32 v[80:81], 0
	v_mov_b64_e32 v[82:83], 0
	v_mov_b64_e32 v[84:85], 0
	v_mov_b64_e32 v[86:87], 0
	v_mov_b64_e32 v[88:89], 0
	v_mov_b64_e32 v[90:91], 0
	v_mov_b64_e32 v[92:93], 0
	v_mov_b64_e32 v[94:95], 0
	v_mov_b64_e32 v[96:97], 0
	v_mov_b64_e32 v[98:99], 0
	v_mov_b64_e32 v[100:101], 0
	v_mov_b64_e32 v[102:103], 0
	v_mov_b64_e32 v[104:105], 0
	v_mov_b64_e32 v[106:107], 0
	v_mov_b64_e32 v[108:109], 0
	v_mov_b64_e32 v[110:111], 0
	v_mov_b64_e32 v[112:113], 0
	v_mov_b64_e32 v[114:115], 0
	v_mov_b64_e32 v[116:117], 0
	v_mov_b64_e32 v[118:119], 0
	v_mov_b64_e32 v[120:121], 0
	v_mov_b64_e32 v[122:123], 0
	v_mov_b64_e32 v[124:125], 0
	v_mov_b64_e32 v[126:127], 0

.LBB0_1705:
	s_mov_b32 s31, s13
	s_lshl_b64 s[34:35], s[30:31], 1
	s_add_u32 s34, s60, s34
	s_addc_u32 s35, s61, s35
	s_and_b64 s[38:39], exec, s[10:11]
	s_cselect_b32 s12, s35, s9
	s_cselect_b32 s15, s34, s8
	s_lshl_b64 s[36:37], s[36:37], 1
	s_add_u32 s36, s29, s36
	s_addc_u32 s37, s54, s37
	s_and_b64 s[10:11], exec, s[10:11]
	s_cselect_b32 s31, s37, s7
	s_cselect_b32 s41, s36, s6
	s_add_u32 s42, s6, 0x80000
	s_addc_u32 s43, s7, 0
	s_add_u32 s6, s8, 0x404000
	v_mov_b32_e32 v56, 0
	s_addc_u32 s7, s9, 0
	s_mov_b32 s44, -2
	v_mov_b64_e32 v[0:1], 0
	v_mov_b64_e32 v[2:3], 0
	v_mov_b64_e32 v[4:5], 0
	v_mov_b64_e32 v[6:7], 0
	v_mov_b64_e32 v[8:9], 0
	v_mov_b64_e32 v[10:11], 0
	v_mov_b64_e32 v[12:13], 0
	v_mov_b64_e32 v[14:15], 0
	v_mov_b64_e32 v[16:17], 0
	v_mov_b64_e32 v[18:19], 0
	v_mov_b64_e32 v[20:21], 0
	v_mov_b64_e32 v[22:23], 0
	v_mov_b64_e32 v[24:25], 0
	v_mov_b64_e32 v[26:27], 0
	v_mov_b64_e32 v[28:29], 0
	v_mov_b64_e32 v[30:31], 0
	v_mov_b64_e32 v[32:33], 0
	v_mov_b64_e32 v[34:35], 0
	v_mov_b64_e32 v[36:37], 0
	v_mov_b64_e32 v[38:39], 0
	v_mov_b64_e32 v[40:41], 0
	v_mov_b64_e32 v[42:43], 0
	v_mov_b64_e32 v[44:45], 0
	v_mov_b64_e32 v[46:47], 0
	v_mov_b64_e32 v[48:49], 0
	v_mov_b64_e32 v[50:51], 0
	v_mov_b64_e32 v[52:53], 0
	v_mov_b64_e32 v[54:55], 0
	v_mov_b32_e32 v57, 0
	v_mov_b64_e32 v[58:59], 0
	v_mov_b64_e32 v[60:61], 0
	v_mov_b64_e32 v[62:63], 0
	v_mov_b64_e32 v[64:65], 0
	v_mov_b64_e32 v[66:67], 0
	v_mov_b64_e32 v[68:69], 0
	v_mov_b64_e32 v[70:71], 0
	v_mov_b64_e32 v[72:73], 0
	v_mov_b64_e32 v[74:75], 0
	v_mov_b64_e32 v[76:77], 0
	v_mov_b64_e32 v[78:79], 0
	v_mov_b64_e32 v[80:81], 0
	v_mov_b64_e32 v[82:83], 0
	v_mov_b64_e32 v[84:85], 0
	v_mov_b64_e32 v[86:87], 0
	v_mov_b64_e32 v[88:89], 0
	v_mov_b64_e32 v[90:91], 0
	v_mov_b64_e32 v[92:93], 0
	v_mov_b64_e32 v[94:95], 0
	v_mov_b64_e32 v[96:97], 0
	v_mov_b64_e32 v[98:99], 0
	v_mov_b64_e32 v[100:101], 0
	v_mov_b64_e32 v[102:103], 0
	v_mov_b64_e32 v[104:105], 0
	v_mov_b64_e32 v[106:107], 0
	v_mov_b64_e32 v[108:109], 0
	v_mov_b64_e32 v[110:111], 0
	v_mov_b64_e32 v[112:113], 0
	v_mov_b64_e32 v[114:115], 0
	v_mov_b64_e32 v[116:117], 0
	v_mov_b64_e32 v[118:119], 0
	v_mov_b64_e32 v[120:121], 0
	v_mov_b64_e32 v[122:123], 0
	v_mov_b64_e32 v[124:125], 0
	v_mov_b64_e32 v[126:127], 0

.LBB0_1998:
	s_mov_b32 s17, s9
	s_lshl_b64 s[20:21], s[16:17], 1
	s_add_u32 s20, s58, s20
	s_addc_u32 s21, s59, s21
	s_and_b64 s[22:23], s[6:7], exec
	s_mov_b32 s19, s9
	s_cselect_b32 s17, s21, s27
	s_cselect_b32 s51, s20, s26
	s_lshl_b64 s[22:23], s[18:19], 1
	s_add_u32 s22, s4, s22
	s_addc_u32 s23, s5, s23
	s_and_b64 s[28:29], s[6:7], exec
	s_cselect_b32 s19, s23, s25
	s_cselect_b32 s52, s22, s24
	s_add_u32 s53, s24, 0x1b0000
	s_addc_u32 s54, s25, 0
	s_add_u32 s24, s26, 0x404000
	v_mov_b32_e32 v32, 0
	s_addc_u32 s25, s27, 0
	s_mov_b32 s55, -2
	v_mov_b64_e32 v[0:1], 0
	v_mov_b64_e32 v[2:3], 0
	v_mov_b64_e32 v[4:5], 0
	v_mov_b64_e32 v[6:7], 0
	v_mov_b64_e32 v[8:9], 0
	v_mov_b64_e32 v[10:11], 0
	v_mov_b64_e32 v[12:13], 0
	v_mov_b64_e32 v[14:15], 0
	v_mov_b64_e32 v[16:17], 0
	v_mov_b64_e32 v[18:19], 0
	v_mov_b64_e32 v[20:21], 0
	v_mov_b64_e32 v[22:23], 0
	v_mov_b64_e32 v[24:25], 0
	v_mov_b64_e32 v[26:27], 0
	v_mov_b64_e32 v[28:29], 0
	v_mov_b64_e32 v[30:31], 0
	v_mov_b32_e32 v33, 0
	v_mov_b64_e32 v[34:35], 0
	v_mov_b64_e32 v[36:37], 0
	v_mov_b64_e32 v[38:39], 0
	v_mov_b64_e32 v[40:41], 0
	v_mov_b64_e32 v[42:43], 0
	v_mov_b64_e32 v[44:45], 0
	v_mov_b64_e32 v[46:47], 0
	v_mov_b64_e32 v[48:49], 0
	v_mov_b64_e32 v[50:51], 0
	v_mov_b64_e32 v[52:53], 0
	v_mov_b64_e32 v[54:55], 0
	v_mov_b64_e32 v[56:57], 0
	v_mov_b64_e32 v[58:59], 0
	v_mov_b64_e32 v[60:61], 0
	v_mov_b64_e32 v[62:63], 0
	v_mov_b64_e32 v[64:65], 0
	v_mov_b64_e32 v[66:67], 0
	v_mov_b64_e32 v[68:69], 0
	v_mov_b64_e32 v[70:71], 0
	v_mov_b64_e32 v[72:73], 0
	v_mov_b64_e32 v[74:75], 0
	v_mov_b64_e32 v[76:77], 0
	v_mov_b64_e32 v[78:79], 0
	v_mov_b64_e32 v[80:81], 0
	v_mov_b64_e32 v[82:83], 0
	v_mov_b64_e32 v[84:85], 0
	v_mov_b64_e32 v[86:87], 0
	v_mov_b64_e32 v[88:89], 0
	v_mov_b64_e32 v[90:91], 0
	v_mov_b64_e32 v[92:93], 0
	v_mov_b64_e32 v[94:95], 0
	v_mov_b64_e32 v[96:97], 0
	v_mov_b64_e32 v[98:99], 0
	v_mov_b64_e32 v[100:101], 0
	v_mov_b64_e32 v[102:103], 0
	v_mov_b64_e32 v[104:105], 0
	v_mov_b64_e32 v[106:107], 0
	v_mov_b64_e32 v[108:109], 0
	v_mov_b64_e32 v[110:111], 0
	v_mov_b64_e32 v[112:113], 0
	v_mov_b64_e32 v[114:115], 0
	v_mov_b64_e32 v[116:117], 0
	v_mov_b64_e32 v[118:119], 0
	v_mov_b64_e32 v[120:121], 0
	v_mov_b64_e32 v[122:123], 0
	v_mov_b64_e32 v[124:125], 0
	v_mov_b64_e32 v[126:127], 0

.LBB0_2012:
	v_and_b32_e32 v141, 15, v11
	v_bfe_u32 v140, v11, 4, 2
	v_lshlrev_b32_e32 v15, 6, v141
	v_lshlrev_b32_e32 v11, 2, v11
	s_and_b32 s24, s5, 3
	v_lshl_or_b32 v15, v140, 4, v15
	s_lshl_b32 s10, s4, 13
	v_and_b32_e32 v11, 32, v11
	v_bitop3_b32 v16, v15, s10, v11 bitop3:0xde
	s_lshl_b32 s10, s24, 12
	v_bitop3_b32 v11, v15, s10, v11 bitop3:0xde
	s_mov_b64 s[10:11], 0x80
	s_add_i32 m0, s23, 0x18000
	v_lshl_add_u64 v[6:7], v[6:7], 0, s[10:11]
	s_waitcnt vmcnt(2)
	s_barrier
	global_load_lds_dwordx4 v[6:7], off
	v_lshl_add_u64 v[4:5], v[4:5], 0, s[10:11]
	s_add_i32 m0, s23, 0x1a000
	s_add_i32 s28, s23, 0x8000
	s_add_i32 s29, s23, 0xa000
	global_load_lds_dwordx4 v[4:5], off
	v_lshl_add_u64 v[2:3], v[2:3], 0, s[10:11]
	s_mov_b32 m0, s28
	s_add_u32 s18, s6, 0x80080
	global_load_lds_dwordx4 v[2:3], off
	v_lshl_add_u64 v[0:1], v[0:1], 0, s[10:11]
	s_mov_b32 m0, s29
	s_addc_u32 s19, s7, 0
	global_load_lds_dwordx4 v[0:1], off
	s_add_i32 m0, s23, 0x1c000
	s_nop 0
	global_load_lds_dwordx4 v132, s[18:19]
	s_add_i32 m0, s23, 0x1e000
	s_add_i32 s12, s17, s14
	global_load_lds_dwordx4 v128, s[18:19]
	v_lshlrev_b32_e32 v0, 16, v12
	v_and_b32_e32 v0, 0xfffe0000, v0
	s_lshl_b64 s[12:13], s[12:13], 1
	v_lshl_add_u32 v0, v13, 13, v0
	v_and_b32_e32 v1, 1, v12
	s_add_u32 s12, s48, s12
	v_lshl_or_b32 v0, v1, 6, v0
	s_addc_u32 s13, s49, s13
	v_lshl_add_u32 v0, v14, 1, v0
	v_mov_b32_e32 v1, v133
	v_lshl_add_u64 v[0:1], s[12:13], 0, v[0:1]
	s_mov_b64 s[18:19], 0x21d00080
	v_lshl_add_u64 v[136:137], v[0:1], 0, s[18:19]
	v_lshlrev_b32_e32 v0, 16, v8
	s_add_i32 s15, s15, s14
	v_and_b32_e32 v0, 0xfffe0000, v0
	s_lshl_b32 s14, s15, 1
	v_lshl_add_u32 v0, v9, 13, v0
	v_and_b32_e32 v1, 1, v8
	s_add_u32 s14, s48, s14
	v_lshl_or_b32 v0, v1, 6, v0
	s_addc_u32 s15, s49, 0
	s_waitcnt vmcnt(6)
	v_lshl_add_u32 v0, v10, 1, v0
	v_mov_b32_e32 v1, v133
	s_add_u32 s30, s14, 0x15800100
	v_lshl_add_u64 v[0:1], s[12:13], 0, v[0:1]
	s_addc_u32 s31, s15, 0
	s_add_i32 s36, s57, s16
	s_add_i32 s38, s81, s16
	s_add_i32 s40, s82, s16
	s_add_i32 s42, s83, s16
	v_lshl_add_u64 v[138:139], v[0:1], 0, s[18:19]
	s_mov_b32 s33, -2
	s_mov_b64 s[14:15], 0
	v_add_u32_e32 v142, s57, v11
	v_add_u32_e32 v143, s81, v11
	v_add_u32_e32 v144, 0, v16
	s_add_i32 s34, s23, 0xc000
	s_add_i32 s35, s23, 0xe000
	s_add_i32 s37, s36, 0x2000
	s_add_i32 s39, s38, 0x2000
	v_add_u32_e32 v145, s82, v11
	v_add_u32_e32 v146, s83, v11
	s_add_i32 s41, s40, 0x2000
	s_add_i32 s43, s42, 0x2000
	v_mov_b64_e32 v[0:1], 0
	v_mov_b64_e32 v[2:3], 0
	v_mov_b64_e32 v[4:5], 0
	v_mov_b64_e32 v[6:7], 0
	v_mov_b64_e32 v[8:9], 0
	v_mov_b64_e32 v[10:11], 0
	v_mov_b64_e32 v[12:13], 0
	v_mov_b64_e32 v[14:15], 0
	v_mov_b64_e32 v[16:17], 0
	v_mov_b64_e32 v[18:19], 0
	v_mov_b64_e32 v[20:21], 0
	v_mov_b64_e32 v[22:23], 0
	v_mov_b64_e32 v[24:25], 0
	v_mov_b64_e32 v[26:27], 0
	v_mov_b64_e32 v[28:29], 0
	v_mov_b64_e32 v[30:31], 0
	v_mov_b64_e32 v[32:33], 0
	v_mov_b64_e32 v[34:35], 0
	v_mov_b64_e32 v[36:37], 0
	v_mov_b64_e32 v[38:39], 0
	v_mov_b64_e32 v[40:41], 0
	v_mov_b64_e32 v[42:43], 0
	v_mov_b64_e32 v[44:45], 0
	v_mov_b64_e32 v[46:47], 0
	v_mov_b64_e32 v[48:49], 0
	v_mov_b64_e32 v[50:51], 0
	v_mov_b64_e32 v[52:53], 0
	v_mov_b64_e32 v[54:55], 0
	v_mov_b64_e32 v[56:57], 0
	v_mov_b64_e32 v[58:59], 0
	v_mov_b64_e32 v[60:61], 0
	v_mov_b64_e32 v[62:63], 0
	v_mov_b64_e32 v[64:65], 0
	v_mov_b64_e32 v[66:67], 0
	v_mov_b64_e32 v[68:69], 0
	v_mov_b64_e32 v[70:71], 0
	v_mov_b64_e32 v[72:73], 0
	v_mov_b64_e32 v[74:75], 0
	v_mov_b64_e32 v[76:77], 0
	v_mov_b64_e32 v[78:79], 0
	v_mov_b64_e32 v[80:81], 0
	v_mov_b64_e32 v[82:83], 0
	v_mov_b64_e32 v[84:85], 0
	v_mov_b64_e32 v[86:87], 0
	v_mov_b64_e32 v[88:89], 0
	v_mov_b64_e32 v[90:91], 0
	v_mov_b64_e32 v[92:93], 0
	v_mov_b64_e32 v[94:95], 0
	v_mov_b64_e32 v[96:97], 0
	v_mov_b64_e32 v[98:99], 0
	v_mov_b64_e32 v[100:101], 0
	v_mov_b64_e32 v[102:103], 0
	v_mov_b64_e32 v[104:105], 0
	v_mov_b64_e32 v[106:107], 0
	v_mov_b64_e32 v[108:109], 0
	v_mov_b64_e32 v[110:111], 0
	v_mov_b64_e32 v[112:113], 0
	v_mov_b64_e32 v[114:115], 0
	v_mov_b64_e32 v[116:117], 0
	v_mov_b64_e32 v[118:119], 0
	v_mov_b64_e32 v[120:121], 0
	v_mov_b64_e32 v[122:123], 0
	v_mov_b64_e32 v[124:125], 0
	v_mov_b64_e32 v[126:127], 0
	s_barrier

.LBB0_2020:
	v_and_b32_e32 v141, 15, v7
	v_bfe_u32 v140, v7, 4, 2
	v_lshlrev_b32_e32 v11, 6, v141
	v_lshlrev_b32_e32 v7, 2, v7
	s_and_b32 s3, s5, 3
	v_lshl_or_b32 v11, v140, 4, v11
	s_lshl_b32 s10, s4, 13
	v_and_b32_e32 v7, 32, v7
	v_bitop3_b32 v14, v11, s10, v7 bitop3:0xde
	s_lshl_b32 s10, s3, 12
	v_bitop3_b32 v7, v11, s10, v7 bitop3:0xde
	s_add_u32 s10, s12, 0x1080
	s_addc_u32 s11, s13, 0
	s_add_i32 m0, s2, 0x18000
	s_waitcnt vmcnt(2)
	s_barrier
	global_load_lds_dwordx4 v132, s[10:11]
	v_lshl_add_u64 v[12:13], s[10:11], 0, v[128:129]
	s_add_i32 m0, s2, 0x1a000
	s_mov_b64 s[10:11], 0x80
	s_add_i32 s26, s2, 0x8000
	s_add_i32 s27, s2, 0xa000
	global_load_lds_dwordx4 v[12:13], off
	v_lshl_add_u64 v[2:3], v[2:3], 0, s[10:11]
	s_mov_b32 m0, s26
	s_add_u32 s12, s12, 0x101080
	global_load_lds_dwordx4 v[2:3], off
	v_lshl_add_u64 v[0:1], v[0:1], 0, s[10:11]
	s_mov_b32 m0, s27
	s_addc_u32 s13, s13, 0
	global_load_lds_dwordx4 v[0:1], off
	s_add_i32 m0, s2, 0x1c000
	s_nop 0
	global_load_lds_dwordx4 v132, s[12:13]
	v_lshl_add_u64 v[0:1], s[12:13], 0, v[128:129]
	s_add_i32 m0, s2, 0x1e000
	s_add_i32 s12, s21, s22
	global_load_lds_dwordx4 v[0:1], off
	v_lshlrev_b32_e32 v0, 15, v8
	v_and_b32_e32 v0, 0xffff0000, v0
	s_lshl_b32 s12, s12, 1
	v_lshl_add_u32 v0, v9, 12, v0
	v_and_b32_e32 v1, 1, v8
	s_add_u32 s12, s48, s12
	v_lshl_or_b32 v0, v1, 6, v0
	s_addc_u32 s13, s49, 0
	v_lshl_add_u32 v0, v10, 1, v0
	v_mov_b32_e32 v1, v133
	v_lshl_add_u64 v[0:1], s[12:13], 0, v[0:1]
	s_mov_b64 s[18:19], 0x18880080
	v_lshl_add_u64 v[136:137], v[0:1], 0, s[18:19]
	v_lshlrev_b32_e32 v0, 15, v4
	s_add_i32 s14, s17, s22
	v_and_b32_e32 v0, 0xffff0000, v0
	s_lshl_b64 s[14:15], s[14:15], 1
	v_lshl_add_u32 v0, v5, 12, v0
	v_and_b32_e32 v1, 1, v4
	s_add_u32 s14, s48, s14
	v_lshl_or_b32 v0, v1, 6, v0
	s_addc_u32 s15, s49, s15
	s_waitcnt vmcnt(6)
	v_lshl_add_u32 v0, v6, 1, v0
	v_mov_b32_e32 v1, v133
	s_add_u32 s28, s14, 0x21c01100
	v_lshl_add_u64 v[0:1], s[12:13], 0, v[0:1]
	s_addc_u32 s29, s15, 0
	s_add_i32 s34, s57, s16
	s_add_i32 s36, s81, s16
	s_add_i32 s38, s82, s16
	s_add_i32 s40, s83, s16
	v_lshl_add_u64 v[138:139], v[0:1], 0, s[18:19]
	s_mov_b32 s30, -2
	s_mov_b64 s[14:15], 0
	v_add_u32_e32 v142, s57, v7
	v_add_u32_e32 v143, s81, v7
	v_add_u32_e32 v144, 0, v14
	s_add_i32 s31, s2, 0xc000
	s_add_i32 s33, s2, 0xe000
	s_add_i32 s35, s34, 0x2000
	s_add_i32 s37, s36, 0x2000
	v_add_u32_e32 v145, s82, v7
	v_add_u32_e32 v146, s83, v7
	s_add_i32 s39, s38, 0x2000
	s_add_i32 s41, s40, 0x2000
	v_mov_b64_e32 v[0:1], 0
	v_mov_b64_e32 v[2:3], 0
	v_mov_b64_e32 v[4:5], 0
	v_mov_b64_e32 v[6:7], 0
	v_mov_b64_e32 v[8:9], 0
	v_mov_b64_e32 v[10:11], 0
	v_mov_b64_e32 v[12:13], 0
	v_mov_b64_e32 v[14:15], 0
	v_mov_b64_e32 v[16:17], 0
	v_mov_b64_e32 v[18:19], 0
	v_mov_b64_e32 v[20:21], 0
	v_mov_b64_e32 v[22:23], 0
	v_mov_b64_e32 v[24:25], 0
	v_mov_b64_e32 v[26:27], 0
	v_mov_b64_e32 v[28:29], 0
	v_mov_b64_e32 v[30:31], 0
	v_mov_b64_e32 v[32:33], 0
	v_mov_b64_e32 v[34:35], 0
	v_mov_b64_e32 v[36:37], 0
	v_mov_b64_e32 v[38:39], 0
	v_mov_b64_e32 v[40:41], 0
	v_mov_b64_e32 v[42:43], 0
	v_mov_b64_e32 v[44:45], 0
	v_mov_b64_e32 v[46:47], 0
	v_mov_b64_e32 v[48:49], 0
	v_mov_b64_e32 v[50:51], 0
	v_mov_b64_e32 v[52:53], 0
	v_mov_b64_e32 v[54:55], 0
	v_mov_b64_e32 v[56:57], 0
	v_mov_b64_e32 v[58:59], 0
	v_mov_b64_e32 v[60:61], 0
	v_mov_b64_e32 v[62:63], 0
	v_mov_b64_e32 v[64:65], 0
	v_mov_b64_e32 v[66:67], 0
	v_mov_b64_e32 v[68:69], 0
	v_mov_b64_e32 v[70:71], 0
	v_mov_b64_e32 v[72:73], 0
	v_mov_b64_e32 v[74:75], 0
	v_mov_b64_e32 v[76:77], 0
	v_mov_b64_e32 v[78:79], 0
	v_mov_b64_e32 v[80:81], 0
	v_mov_b64_e32 v[82:83], 0
	v_mov_b64_e32 v[84:85], 0
	v_mov_b64_e32 v[86:87], 0
	v_mov_b64_e32 v[88:89], 0
	v_mov_b64_e32 v[90:91], 0
	v_mov_b64_e32 v[92:93], 0
	v_mov_b64_e32 v[94:95], 0
	v_mov_b64_e32 v[96:97], 0
	v_mov_b64_e32 v[98:99], 0
	v_mov_b64_e32 v[100:101], 0
	v_mov_b64_e32 v[102:103], 0
	v_mov_b64_e32 v[104:105], 0
	v_mov_b64_e32 v[106:107], 0
	v_mov_b64_e32 v[108:109], 0
	v_mov_b64_e32 v[110:111], 0
	v_mov_b64_e32 v[112:113], 0
	v_mov_b64_e32 v[114:115], 0
	v_mov_b64_e32 v[116:117], 0
	v_mov_b64_e32 v[118:119], 0
	v_mov_b64_e32 v[120:121], 0
	v_mov_b64_e32 v[122:123], 0
	v_mov_b64_e32 v[124:125], 0
	v_mov_b64_e32 v[126:127], 0
	s_barrier

.LBB0_2541:
	s_mov_b32 s29, s11
	s_lshl_b64 s[30:31], s[28:29], 1
	s_add_u32 s30, s64, s30
	s_addc_u32 s31, s65, s31
	s_and_b64 s[36:37], exec, s[8:9]
	s_cselect_b32 s10, s31, s7
	s_cselect_b32 s13, s30, s6
	s_lshl_b64 s[34:35], s[34:35], 1
	s_add_u32 s34, s2, s34
	s_addc_u32 s35, s3, s35
	s_and_b64 s[8:9], exec, s[8:9]
	s_cselect_b32 s29, s35, s1
	s_cselect_b32 s39, s34, s0
	s_add_u32 s40, s0, 0x80000
	s_addc_u32 s41, s1, 0
	s_add_u32 s0, s6, 0x404000
	v_mov_b32_e32 v56, 0
	s_addc_u32 s1, s7, 0
	s_mov_b32 s42, -2
	v_mov_b64_e32 v[0:1], 0
	v_mov_b64_e32 v[2:3], 0
	v_mov_b64_e32 v[4:5], 0
	v_mov_b64_e32 v[6:7], 0
	v_mov_b64_e32 v[8:9], 0
	v_mov_b64_e32 v[10:11], 0
	v_mov_b64_e32 v[12:13], 0
	v_mov_b64_e32 v[14:15], 0
	v_mov_b64_e32 v[16:17], 0
	v_mov_b64_e32 v[18:19], 0
	v_mov_b64_e32 v[20:21], 0
	v_mov_b64_e32 v[22:23], 0
	v_mov_b64_e32 v[24:25], 0
	v_mov_b64_e32 v[26:27], 0
	v_mov_b64_e32 v[28:29], 0
	v_mov_b64_e32 v[30:31], 0
	v_mov_b64_e32 v[32:33], 0
	v_mov_b64_e32 v[34:35], 0
	v_mov_b64_e32 v[36:37], 0
	v_mov_b64_e32 v[38:39], 0
	v_mov_b64_e32 v[40:41], 0
	v_mov_b64_e32 v[42:43], 0
	v_mov_b64_e32 v[44:45], 0
	v_mov_b64_e32 v[46:47], 0
	v_mov_b64_e32 v[48:49], 0
	v_mov_b64_e32 v[50:51], 0
	v_mov_b64_e32 v[52:53], 0
	v_mov_b64_e32 v[54:55], 0
	v_mov_b32_e32 v57, 0
	v_mov_b64_e32 v[58:59], 0
	v_mov_b64_e32 v[60:61], 0
	v_mov_b64_e32 v[62:63], 0
	v_mov_b64_e32 v[64:65], 0
	v_mov_b64_e32 v[66:67], 0
	v_mov_b64_e32 v[68:69], 0
	v_mov_b64_e32 v[70:71], 0
	v_mov_b64_e32 v[72:73], 0
	v_mov_b64_e32 v[74:75], 0
	v_mov_b64_e32 v[76:77], 0
	v_mov_b64_e32 v[78:79], 0
	v_mov_b64_e32 v[80:81], 0
	v_mov_b64_e32 v[82:83], 0
	v_mov_b64_e32 v[84:85], 0
	v_mov_b64_e32 v[86:87], 0
	v_mov_b64_e32 v[88:89], 0
	v_mov_b64_e32 v[90:91], 0
	v_mov_b64_e32 v[92:93], 0
	v_mov_b64_e32 v[94:95], 0
	v_mov_b64_e32 v[96:97], 0
	v_mov_b64_e32 v[98:99], 0
	v_mov_b64_e32 v[100:101], 0
	v_mov_b64_e32 v[102:103], 0
	v_mov_b64_e32 v[104:105], 0
	v_mov_b64_e32 v[106:107], 0
	v_mov_b64_e32 v[108:109], 0
	v_mov_b64_e32 v[110:111], 0
	v_mov_b64_e32 v[112:113], 0
	v_mov_b64_e32 v[114:115], 0
	v_mov_b64_e32 v[116:117], 0
	v_mov_b64_e32 v[118:119], 0
	v_mov_b64_e32 v[120:121], 0
	v_mov_b64_e32 v[122:123], 0
	v_mov_b64_e32 v[124:125], 0
	v_mov_b64_e32 v[126:127], 0

.LBB0_2663:
	s_mov_b32 s15, s7
	s_lshl_b64 s[18:19], s[14:15], 1
	s_add_u32 s18, s58, s18
	s_addc_u32 s19, s59, s19
	s_and_b64 s[20:21], s[0:1], exec
	s_mov_b32 s17, s7
	s_cselect_b32 s6, s19, s25
	s_cselect_b32 s15, s18, s24
	s_lshl_b64 s[20:21], s[16:17], 1
	s_add_u32 s20, s79, s20
	v_readlane_b32 s17, v250, 4
	s_addc_u32 s21, s17, s21
	s_and_b64 s[26:27], s[0:1], exec
	s_cselect_b32 s17, s21, s23
	s_cselect_b32 s54, s20, s22
	s_add_u32 s55, s22, 0x100
	s_addc_u32 s56, s23, 0
	s_add_u32 s22, s24, 0x404000
	v_mov_b32_e32 v0, 0
	s_addc_u32 s23, s25, 0
	s_mov_b32 s64, -2
	v_mov_b32_e32 v1, 0
	v_mov_b64_e32 v[2:3], 0
	v_mov_b64_e32 v[4:5], 0
	v_mov_b64_e32 v[6:7], 0
	v_mov_b64_e32 v[8:9], 0
	v_mov_b64_e32 v[10:11], 0
	v_mov_b64_e32 v[12:13], 0
	v_mov_b64_e32 v[14:15], 0
	v_mov_b64_e32 v[16:17], 0
	v_mov_b64_e32 v[18:19], 0
	v_mov_b64_e32 v[20:21], 0
	v_mov_b64_e32 v[22:23], 0
	v_mov_b64_e32 v[24:25], 0
	v_mov_b64_e32 v[26:27], 0
	v_mov_b64_e32 v[28:29], 0
	v_mov_b64_e32 v[30:31], 0
	v_mov_b64_e32 v[32:33], 0
	v_mov_b64_e32 v[34:35], 0
	v_mov_b64_e32 v[36:37], 0
	v_mov_b64_e32 v[38:39], 0
	v_mov_b64_e32 v[40:41], 0
	v_mov_b64_e32 v[42:43], 0
	v_mov_b64_e32 v[44:45], 0
	v_mov_b64_e32 v[46:47], 0
	v_mov_b64_e32 v[48:49], 0
	v_mov_b64_e32 v[50:51], 0
	v_mov_b64_e32 v[52:53], 0
	v_mov_b64_e32 v[54:55], 0
	v_mov_b64_e32 v[56:57], 0
	v_mov_b64_e32 v[58:59], 0
	v_mov_b64_e32 v[60:61], 0
	v_mov_b64_e32 v[62:63], 0
	v_mov_b64_e32 v[64:65], 0
	v_mov_b64_e32 v[66:67], 0
	v_mov_b64_e32 v[68:69], 0
	v_mov_b64_e32 v[70:71], 0
	v_mov_b64_e32 v[72:73], 0
	v_mov_b64_e32 v[74:75], 0
	v_mov_b64_e32 v[76:77], 0
	v_mov_b64_e32 v[78:79], 0
	v_mov_b64_e32 v[80:81], 0
	v_mov_b64_e32 v[82:83], 0
	v_mov_b64_e32 v[84:85], 0
	v_mov_b64_e32 v[86:87], 0
	v_mov_b64_e32 v[88:89], 0
	v_mov_b64_e32 v[90:91], 0
	v_mov_b64_e32 v[92:93], 0
	v_mov_b64_e32 v[94:95], 0
	v_mov_b64_e32 v[96:97], 0
	v_mov_b64_e32 v[98:99], 0
	v_mov_b64_e32 v[100:101], 0
	v_mov_b64_e32 v[102:103], 0
	v_mov_b64_e32 v[104:105], 0
	v_mov_b64_e32 v[106:107], 0
	v_mov_b64_e32 v[108:109], 0
	v_mov_b64_e32 v[110:111], 0
	v_mov_b64_e32 v[112:113], 0
	v_mov_b64_e32 v[114:115], 0
	v_mov_b64_e32 v[116:117], 0
	v_mov_b64_e32 v[118:119], 0
	v_mov_b64_e32 v[120:121], 0
	v_mov_b64_e32 v[122:123], 0
	v_mov_b64_e32 v[124:125], 0
	v_mov_b64_e32 v[126:127], 0

.LBB0_2771:
	s_mov_b32 s27, s11
	s_lshl_b64 s[30:31], s[26:27], 1
	s_add_u32 s30, s91, s30
	s_addc_u32 s31, s92, s31
	s_and_b64 s[34:35], s[8:9], exec
	s_mov_b32 s29, s11
	s_cselect_b32 s10, s31, s7
	s_cselect_b32 s13, s30, s6
	s_lshl_b64 s[34:35], s[28:29], 1
	s_add_u32 s34, s80, s34
	s_addc_u32 s35, s86, s35
	s_and_b64 s[8:9], s[8:9], exec
	s_cselect_b32 s27, s35, s1
	s_cselect_b32 s29, s34, s0
	s_add_u32 s39, s0, 0x100
	s_addc_u32 s40, s1, 0
	s_add_u32 s0, s6, 0x404000
	v_mov_b32_e32 v56, 0
	s_addc_u32 s1, s7, 0
	s_mov_b32 s41, -2
	v_mov_b64_e32 v[0:1], 0
	v_mov_b64_e32 v[2:3], 0
	v_mov_b64_e32 v[4:5], 0
	v_mov_b64_e32 v[6:7], 0
	v_mov_b64_e32 v[8:9], 0
	v_mov_b64_e32 v[10:11], 0
	v_mov_b64_e32 v[12:13], 0
	v_mov_b64_e32 v[14:15], 0
	v_mov_b64_e32 v[16:17], 0
	v_mov_b64_e32 v[18:19], 0
	v_mov_b64_e32 v[20:21], 0
	v_mov_b64_e32 v[22:23], 0
	v_mov_b64_e32 v[24:25], 0
	v_mov_b64_e32 v[26:27], 0
	v_mov_b64_e32 v[28:29], 0
	v_mov_b64_e32 v[30:31], 0
	v_mov_b64_e32 v[32:33], 0
	v_mov_b64_e32 v[34:35], 0
	v_mov_b64_e32 v[36:37], 0
	v_mov_b64_e32 v[38:39], 0
	v_mov_b64_e32 v[40:41], 0
	v_mov_b64_e32 v[42:43], 0
	v_mov_b64_e32 v[44:45], 0
	v_mov_b64_e32 v[46:47], 0
	v_mov_b64_e32 v[48:49], 0
	v_mov_b64_e32 v[50:51], 0
	v_mov_b64_e32 v[52:53], 0
	v_mov_b64_e32 v[54:55], 0
	v_mov_b32_e32 v57, 0
	v_mov_b64_e32 v[58:59], 0
	v_mov_b64_e32 v[60:61], 0
	v_mov_b64_e32 v[62:63], 0
	v_mov_b64_e32 v[64:65], 0
	v_mov_b64_e32 v[66:67], 0
	v_mov_b64_e32 v[68:69], 0
	v_mov_b64_e32 v[70:71], 0
	v_mov_b64_e32 v[72:73], 0
	v_mov_b64_e32 v[74:75], 0
	v_mov_b64_e32 v[76:77], 0
	v_mov_b64_e32 v[78:79], 0
	v_mov_b64_e32 v[80:81], 0
	v_mov_b64_e32 v[82:83], 0
	v_mov_b64_e32 v[84:85], 0
	v_mov_b64_e32 v[86:87], 0
	v_mov_b64_e32 v[88:89], 0
	v_mov_b64_e32 v[90:91], 0
	v_mov_b64_e32 v[92:93], 0
	v_mov_b64_e32 v[94:95], 0
	v_mov_b64_e32 v[96:97], 0
	v_mov_b64_e32 v[98:99], 0
	v_mov_b64_e32 v[100:101], 0
	v_mov_b64_e32 v[102:103], 0
	v_mov_b64_e32 v[104:105], 0
	v_mov_b64_e32 v[106:107], 0
	v_mov_b64_e32 v[108:109], 0
	v_mov_b64_e32 v[110:111], 0
	v_mov_b64_e32 v[112:113], 0
	v_mov_b64_e32 v[114:115], 0
	v_mov_b64_e32 v[116:117], 0
	v_mov_b64_e32 v[118:119], 0
	v_mov_b64_e32 v[120:121], 0
	v_mov_b64_e32 v[122:123], 0
	v_mov_b64_e32 v[124:125], 0
	v_mov_b64_e32 v[126:127], 0

.LBB0_2887:
	s_mov_b32 s15, s7
	s_lshl_b64 s[18:19], s[14:15], 1
	s_add_u32 s18, s58, s18
	s_addc_u32 s19, s59, s19
	s_and_b64 s[20:21], s[0:1], exec
	s_mov_b32 s17, s7
	s_cselect_b32 s15, s19, s25
	s_cselect_b32 s50, s18, s24
	s_lshl_b64 s[20:21], s[16:17], 1
	s_add_u32 s20, s4, s20
	s_addc_u32 s21, s5, s21
	s_and_b64 s[26:27], s[0:1], exec
	s_cselect_b32 s17, s21, s23
	s_cselect_b32 s51, s20, s22
	s_add_u32 s52, s22, 0x2c0000
	s_addc_u32 s53, s23, 0
	s_add_u32 s22, s24, 0x404000
	v_mov_b32_e32 v0, 0
	s_addc_u32 s23, s25, 0
	s_mov_b32 s54, -2
	v_mov_b32_e32 v1, 0
	v_mov_b64_e32 v[2:3], 0
	v_mov_b64_e32 v[4:5], 0
	v_mov_b64_e32 v[6:7], 0
	v_mov_b64_e32 v[8:9], 0
	v_mov_b64_e32 v[10:11], 0
	v_mov_b64_e32 v[12:13], 0
	v_mov_b64_e32 v[14:15], 0
	v_mov_b64_e32 v[16:17], 0
	v_mov_b64_e32 v[18:19], 0
	v_mov_b64_e32 v[20:21], 0
	v_mov_b64_e32 v[22:23], 0
	v_mov_b64_e32 v[24:25], 0
	v_mov_b64_e32 v[26:27], 0
	v_mov_b64_e32 v[28:29], 0
	v_mov_b64_e32 v[30:31], 0
	v_mov_b64_e32 v[32:33], 0
	v_mov_b64_e32 v[34:35], 0
	v_mov_b64_e32 v[36:37], 0
	v_mov_b64_e32 v[38:39], 0
	v_mov_b64_e32 v[40:41], 0
	v_mov_b64_e32 v[42:43], 0
	v_mov_b64_e32 v[44:45], 0
	v_mov_b64_e32 v[46:47], 0
	v_mov_b64_e32 v[48:49], 0
	v_mov_b64_e32 v[50:51], 0
	v_mov_b64_e32 v[52:53], 0
	v_mov_b64_e32 v[54:55], 0
	v_mov_b64_e32 v[56:57], 0
	v_mov_b64_e32 v[58:59], 0
	v_mov_b64_e32 v[60:61], 0
	v_mov_b64_e32 v[62:63], 0
	v_mov_b64_e32 v[64:65], 0
	v_mov_b64_e32 v[66:67], 0
	v_mov_b64_e32 v[68:69], 0
	v_mov_b64_e32 v[70:71], 0
	v_mov_b64_e32 v[72:73], 0
	v_mov_b64_e32 v[74:75], 0
	v_mov_b64_e32 v[76:77], 0
	v_mov_b64_e32 v[78:79], 0
	v_mov_b64_e32 v[80:81], 0
	v_mov_b64_e32 v[82:83], 0
	v_mov_b64_e32 v[84:85], 0
	v_mov_b64_e32 v[86:87], 0
	v_mov_b64_e32 v[88:89], 0
	v_mov_b64_e32 v[90:91], 0
	v_mov_b64_e32 v[92:93], 0
	v_mov_b64_e32 v[94:95], 0
	v_mov_b64_e32 v[96:97], 0
	v_mov_b64_e32 v[98:99], 0
	v_mov_b64_e32 v[100:101], 0
	v_mov_b64_e32 v[102:103], 0
	v_mov_b64_e32 v[104:105], 0
	v_mov_b64_e32 v[106:107], 0
	v_mov_b64_e32 v[108:109], 0
	v_mov_b64_e32 v[110:111], 0
	v_mov_b64_e32 v[112:113], 0
	v_mov_b64_e32 v[114:115], 0
	v_mov_b64_e32 v[116:117], 0
	v_mov_b64_e32 v[118:119], 0
	v_mov_b64_e32 v[120:121], 0
	v_mov_b64_e32 v[122:123], 0
	v_mov_b64_e32 v[124:125], 0
	v_mov_b64_e32 v[126:127], 0

.LBB0_2965:
	s_mov_b32 s25, s7
	s_lshl_b64 s[26:27], s[24:25], 1
	s_add_u32 s26, s60, s26
	s_addc_u32 s27, s61, s27
	s_and_b64 s[34:35], exec, s[4:5]
	s_cselect_b32 s6, s27, s3
	s_cselect_b32 s9, s26, s2
	s_lshl_b64 s[28:29], s[28:29], 1
	s_add_u32 s28, s23, s28
	s_addc_u32 s29, s44, s29
	s_and_b64 s[4:5], exec, s[4:5]
	s_cselect_b32 s25, s29, s1
	s_cselect_b32 s36, s28, s0
	s_add_u32 s37, s0, 0x80000
	s_addc_u32 s38, s1, 0
	s_add_u32 s0, s2, 0x404000
	v_mov_b32_e32 v88, 0
	s_addc_u32 s1, s3, 0
	s_mov_b32 s39, -2
	v_mov_b64_e32 v[0:1], 0
	v_mov_b64_e32 v[2:3], 0
	v_mov_b64_e32 v[4:5], 0
	v_mov_b64_e32 v[6:7], 0
	v_mov_b64_e32 v[8:9], 0
	v_mov_b64_e32 v[10:11], 0
	v_mov_b64_e32 v[12:13], 0
	v_mov_b64_e32 v[14:15], 0
	v_mov_b64_e32 v[16:17], 0
	v_mov_b64_e32 v[18:19], 0
	v_mov_b64_e32 v[20:21], 0
	v_mov_b64_e32 v[22:23], 0
	v_mov_b64_e32 v[24:25], 0
	v_mov_b64_e32 v[26:27], 0
	v_mov_b64_e32 v[28:29], 0
	v_mov_b64_e32 v[30:31], 0
	v_mov_b64_e32 v[32:33], 0
	v_mov_b64_e32 v[34:35], 0
	v_mov_b64_e32 v[36:37], 0
	v_mov_b64_e32 v[38:39], 0
	v_mov_b64_e32 v[40:41], 0
	v_mov_b64_e32 v[42:43], 0
	v_mov_b64_e32 v[44:45], 0
	v_mov_b64_e32 v[46:47], 0
	v_mov_b64_e32 v[48:49], 0
	v_mov_b64_e32 v[50:51], 0
	v_mov_b64_e32 v[52:53], 0
	v_mov_b64_e32 v[54:55], 0
	v_mov_b64_e32 v[56:57], 0
	v_mov_b64_e32 v[58:59], 0
	v_mov_b64_e32 v[60:61], 0
	v_mov_b64_e32 v[62:63], 0
	v_mov_b64_e32 v[64:65], 0
	v_mov_b64_e32 v[66:67], 0
	v_mov_b64_e32 v[68:69], 0
	v_mov_b64_e32 v[70:71], 0
	v_mov_b64_e32 v[72:73], 0
	v_mov_b64_e32 v[74:75], 0
	v_mov_b64_e32 v[76:77], 0
	v_mov_b64_e32 v[78:79], 0
	v_mov_b64_e32 v[80:81], 0
	v_mov_b64_e32 v[82:83], 0
	v_mov_b64_e32 v[84:85], 0
	v_mov_b64_e32 v[86:87], 0
	v_mov_b32_e32 v89, 0
	v_mov_b64_e32 v[90:91], 0
	v_mov_b64_e32 v[92:93], 0
	v_mov_b64_e32 v[94:95], 0
	v_mov_b64_e32 v[96:97], 0
	v_mov_b64_e32 v[98:99], 0
	v_mov_b64_e32 v[100:101], 0
	v_mov_b64_e32 v[102:103], 0
	v_mov_b64_e32 v[104:105], 0
	v_mov_b64_e32 v[106:107], 0
	v_mov_b64_e32 v[108:109], 0
	v_mov_b64_e32 v[110:111], 0
	v_mov_b64_e32 v[112:113], 0
	v_mov_b64_e32 v[114:115], 0
	v_mov_b64_e32 v[116:117], 0
	v_mov_b64_e32 v[118:119], 0
	v_mov_b64_e32 v[120:121], 0
	v_mov_b64_e32 v[122:123], 0
	v_mov_b64_e32 v[124:125], 0
	v_mov_b64_e32 v[126:127], 0
